# MLA loop: K/V tile LDS stores moved from the loop tail to mid-iteration (other slot is idle), on top of the de-serialised GEMM epilogues
# baseline (speedup 1.0000x reference)
; #define MLA_STORE(slot) do { unsigned char* sb_ = lds + (slot) * MLA_SLOT; MLA_ST1(sb_, kA0, kB0, vv0); MLA_ST1(sb_ + MLA_BUF, kA1, kB1, vv1); } while (0)
; #define MLA_KL(ka, u) do { const unsigned char* kb_ = sl + ((u) >> 1) * MLA_BUF + (32 * ((u) & 1) + r) * MLA_KP + 16 * h; _Pragma("unroll") for (int s = 0; s < 6; ++s) ka[s] = *(const bf16x8*)(kb_ + 32 * s); } while (0)
; #define MLA_QK(sx, ka) do { sx = zero16(); _Pragma("unroll") for (int s = 0; s < 6; ++s) sx = MFMA32(ka[s], qf[s], sx); } while (0)
; #define MLA_SMF(sx, pa, pb) do { float ps_ = 0.f; _Pragma("unroll") for (int i = 0; i < 16; ++i) { sx[i] = fexp2(sx[i]); ps_ += sx[i]; } lrun += ps_; pa = packp(sx, 0); pb = packp(sx, 1); } while (0)
; #define MLA_PV(va, vc2, pa, pb) do { o0 = MFMA32(va[0], pa, o0); o1 = MFMA32(vc2[0], pa, o1); o0 = MFMA32(va[1], pb, o0); o1 = MFMA32(vc2[1], pb, o1); } while (0)
; #define SB() __builtin_amdgcn_sched_barrier(0)
; template <bool FAST> DI bool mla_unit(unsigned char* lds, unsigned char* ws, int seq, int head, int qb, int S, int tid, int wave, int lane) {
;     ...
;     const int nit = S >> 7;
;     MLA_LOAD(0); MLA_STORE(0); __syncthreads();
;     for (int it = 0; it < nit; ++it) {
;         const unsigned char* sl = lds + (it & 1) * MLA_SLOT;
;         MLA_LOAD(min(it + 1, nit - 1)); SB();
;         if constexpr (FAST) {
;             bf16x8 kaA[6], kaB[6], vaA[2], vcA[2], vaB[2], vcB[2], paA, pbA, paB, pbB; f32x16 sA, sB;
;             MLA_KL(kaA, 0); MLA_KL(kaB, 1);
;             MLA_QK(sA, kaA);
;             MLA_QK(sB, kaB); MLA_SMF(sA, paA, pbA); MLA_VL(vaA, vcA, 0); MLA_KL(kaA, 2);
;             MLA_PV(vaA, vcA, paA, pbA); MLA_QK(sA, kaA); MLA_SMF(sB, paB, pbB); MLA_VL(vaB, vcB, 1); MLA_KL(kaB, 3);
;             MLA_PV(vaB, vcB, paB, pbB); MLA_QK(sB, kaB); MLA_SMF(sA, paA, pbA); MLA_VL(vaA, vcA, 2);
;             MLA_PV(vaA, vcA, paA, pbA); MLA_SMF(sB, paB, pbB); MLA_VL(vaB, vcB, 3);
;             MLA_PV(vaB, vcB, paB, pbB);
.LBB0_1008:
	s_bitcmp1_b32 s3, 0
	s_cselect_b32 s22, 0xac00, 0
	s_add_i32 s3, s3, 1
	s_min_i32 s4, s3, s20
	s_lshl_b32 s4, s4, 7
	v_add_u32_e32 v32, s4, v215
	v_add_u32_e32 v34, s4, v216
	v_mad_i64_i32 v[32:33], s[8:9], v32, s92, v[170:171]
	v_mad_i64_i32 v[34:35], s[8:9], v34, s92, v[172:173]
	global_load_dwordx4 v[92:95], v[32:33], off
	global_load_dwordx4 v[88:91], v[34:35], off
	v_add_co_u32_e32 v32, vcc, s90, v32
	s_ashr_i32 s5, s4, 31
	s_nop 0
	v_addc_co_u32_e32 v33, vcc, 0, v33, vcc
	v_lshl_add_u64 v[36:37], s[4:5], 1, v[168:169]
	v_add_co_u32_e32 v34, vcc, s90, v34
	s_add_i32 s4, s22, 0
	s_nop 0
	v_addc_co_u32_e32 v35, vcc, 0, v35, vcc
	global_load_dwordx4 v[96:99], v[36:37], off
	global_load_dwordx4 v[100:103], v[36:37], off offset:128
	global_load_dwordx4 v[104:107], v[32:33], off
	global_load_dwordx4 v[108:111], v[34:35], off
	v_add3_u32 v177, s4, v221, v222
	ds_read_b128 v[32:35], v177
	ds_read_b128 v[48:51], v177 offset:32
	ds_read_b128 v[52:55], v177 offset:64
	ds_read_b128 v[56:59], v177 offset:96
	ds_read_b128 v[60:63], v177 offset:128
	ds_read_b128 v[112:115], v177 offset:160
	ds_read_b128 v[116:119], v177 offset:6656
	ds_read_b128 v[120:123], v177 offset:6688
	ds_read_b128 v[124:127], v177 offset:6720
	ds_read_b128 v[128:131], v177 offset:6752
	ds_read_b128 v[132:135], v177 offset:6784
	ds_read_b128 v[178:181], v177 offset:6816
	s_waitcnt lgkmcnt(11)
	v_mfma_f32_32x32x16_bf16 v[32:47], v[32:35], v[64:67], 0
	v_add3_u32 v230, s4, v223, v152
	v_add_u32_e32 v199, 0x3000, v230
	v_add_u32_e32 v201, 0x4000, v230
	s_waitcnt lgkmcnt(10)
	v_mfma_f32_32x32x16_bf16 v[32:47], v[48:51], v[68:71], v[32:47]
	s_waitcnt lgkmcnt(9)
	v_mfma_f32_32x32x16_bf16 v[32:47], v[52:55], v[72:75], v[32:47]
	s_waitcnt lgkmcnt(8)
	v_mfma_f32_32x32x16_bf16 v[32:47], v[56:59], v[76:79], v[32:47]
	s_waitcnt lgkmcnt(7)
	v_mfma_f32_32x32x16_bf16 v[32:47], v[60:63], v[80:83], v[32:47]
	s_waitcnt lgkmcnt(6)
	v_mfma_f32_32x32x16_bf16 v[32:47], v[112:115], v[84:87], v[32:47]
	s_nop 11
	v_exp_f32_e32 v48, v32
	v_exp_f32_e32 v49, v33
	v_exp_f32_e32 v50, v34
	v_exp_f32_e32 v51, v35
	v_exp_f32_e32 v52, v36
	v_exp_f32_e32 v53, v37
	v_exp_f32_e32 v54, v38
	v_exp_f32_e32 v55, v39
	v_exp_f32_e32 v56, v40
	v_exp_f32_e32 v57, v41
	v_exp_f32_e32 v58, v42
	v_exp_f32_e32 v59, v43
	v_exp_f32_e32 v60, v44
	v_exp_f32_e32 v61, v45
	v_exp_f32_e32 v62, v46
	v_exp_f32_e32 v63, v47
	s_waitcnt lgkmcnt(5)
	v_mfma_f32_32x32x16_bf16 v[32:47], v[116:119], v[64:67], 0
	v_cvt_pk_bf16_f32 v112, v48, v49
	v_add_f32_e32 v48, 0, v48
	v_add_f32_e32 v48, v49, v48
	v_add_f32_e32 v48, v50, v48
	v_add_f32_e32 v48, v51, v48
	v_add_f32_e32 v48, v52, v48
	v_add_f32_e32 v48, v53, v48
	s_waitcnt lgkmcnt(4)
	v_mfma_f32_32x32x16_bf16 v[32:47], v[120:123], v[68:71], v[32:47]
	v_add_f32_e32 v48, v54, v48
	v_add_f32_e32 v48, v55, v48
	v_add_f32_e32 v48, v56, v48
	v_add_f32_e32 v48, v57, v48
	v_add_f32_e32 v48, v58, v48
	v_add_f32_e32 v48, v59, v48
	v_add_f32_e32 v48, v60, v48
	s_waitcnt lgkmcnt(3)
	v_mfma_f32_32x32x16_bf16 v[32:47], v[124:127], v[72:75], v[32:47]
	v_add_f32_e32 v48, v61, v48
	v_add_f32_e32 v48, v62, v48
	v_cvt_pk_bf16_f32 v113, v50, v51
	v_add_f32_e32 v203, v63, v48
	v_cvt_pk_bf16_f32 v114, v52, v53
	v_cvt_pk_bf16_f32 v115, v54, v55
	v_cvt_pk_bf16_f32 v116, v56, v57
	s_waitcnt lgkmcnt(2)
	v_mfma_f32_32x32x16_bf16 v[32:47], v[128:131], v[76:79], v[32:47]
	v_cvt_pk_bf16_f32 v117, v58, v59
	v_cvt_pk_bf16_f32 v118, v60, v61
	v_cvt_pk_bf16_f32 v119, v62, v63
	s_waitcnt lgkmcnt(1)
	v_mfma_f32_32x32x16_bf16 v[32:47], v[132:135], v[80:83], v[32:47]
	ds_read2_b64 v[132:135], v199 offset0:128 offset1:130
	ds_read2_b64 v[128:131], v199 offset0:132 offset1:134
	ds_read2_b64 v[124:127], v201 offset0:160 offset1:162
	ds_read2_b64 v[120:123], v201 offset0:164 offset1:166
	s_waitcnt lgkmcnt(4)
	v_mfma_f32_32x32x16_bf16 v[32:47], v[178:181], v[84:87], v[32:47]
	ds_read_b128 v[48:51], v177 offset:22016
	ds_read_b128 v[178:181], v177 offset:22048
	ds_read_b128 v[182:185], v177 offset:22080
	ds_read_b128 v[186:189], v177 offset:22112
	ds_read_b128 v[190:193], v177 offset:22144
	ds_read_b128 v[194:197], v177 offset:22176
	s_nop 5
	v_exp_f32_e32 v32, v32
	s_waitcnt lgkmcnt(5)
	v_mfma_f32_32x32x16_bf16 v[48:63], v[48:51], v[64:67], 0
	v_exp_f32_e32 v198, v33
	v_exp_f32_e32 v202, v34
	v_add_f32_e32 v148, 0, v32
	v_exp_f32_e32 v200, v35
	v_exp_f32_e32 v204, v36
	v_exp_f32_e32 v176, v46
	v_exp_f32_e32 v174, v47
	s_waitcnt lgkmcnt(4)
	v_mfma_f32_32x32x16_bf16 v[48:63], v[178:181], v[68:71], v[48:63]
	v_exp_f32_e32 v180, v44
	v_exp_f32_e32 v178, v45
	s_waitcnt lgkmcnt(3)
	v_mfma_f32_32x32x16_bf16 v[48:63], v[182:185], v[72:75], v[48:63]
	v_exp_f32_e32 v184, v42
	v_exp_f32_e32 v182, v43
	s_waitcnt lgkmcnt(2)
	v_mfma_f32_32x32x16_bf16 v[48:63], v[186:189], v[76:79], v[48:63]
	v_exp_f32_e32 v188, v40
	v_exp_f32_e32 v186, v41
	v_mfma_f32_32x32x16_bf16 v[0:15], v[132:135], v[112:115], v[0:15]
	v_mfma_f32_32x32x16_bf16 v[16:31], v[124:127], v[112:115], v[16:31]
	v_cvt_pk_bf16_f32 v112, v32, v198
	v_cvt_pk_bf16_f32 v113, v202, v200
	s_waitcnt lgkmcnt(1)
	v_mfma_f32_32x32x16_bf16 v[48:63], v[190:193], v[80:83], v[48:63]
	v_exp_f32_e32 v192, v38
	v_exp_f32_e32 v190, v39
	s_nop 0
	v_cvt_pk_bf16_f32 v115, v192, v190
	v_mfma_f32_32x32x16_bf16 v[0:15], v[128:131], v[116:119], v[0:15]
	v_mfma_f32_32x32x16_bf16 v[16:31], v[120:123], v[116:119], v[16:31]
	ds_read2_b64 v[128:131], v199 offset0:136 offset1:138
	ds_read2_b64 v[120:123], v201 offset0:168 offset1:170
	ds_read2_b64 v[132:135], v199 offset0:140 offset1:142
	ds_read2_b64 v[124:127], v201 offset0:172 offset1:174
	ds_read_b128 v[32:35], v177 offset:28672
	ds_read_b128 v[234:237], v177 offset:28704
	ds_read_b128 v[238:241], v177 offset:28736
	ds_read_b128 v[242:245], v177 offset:28768
	ds_read_b128 v[246:249], v177 offset:28800
	ds_read_b128 v[250:253], v177 offset:28832
	v_cvt_pk_bf16_f32 v116, v188, v186
	v_cvt_pk_bf16_f32 v117, v184, v182
	v_cvt_pk_bf16_f32 v118, v180, v178
	v_cvt_pk_bf16_f32 v119, v176, v174
	s_waitcnt lgkmcnt(10)
; DI float fexp2(float x) { return __builtin_amdgcn_exp2f(x); }
; DI float shx(float v, int lane, int mask) { return __builtin_bit_cast(float, __builtin_amdgcn_ds_bpermute((lane ^ mask) << 2, __builtin_bit_cast(int, v))); }
; DI float vmax16(const f32x16& s) { return fmaxf(fmaxf(fmaxf(fmaxf(s[0], s[1]), fmaxf(s[2], s[3])), fmaxf(fmaxf(s[4], s[5]), fmaxf(s[6], s[7]))), fmaxf(fmaxf(fmaxf(s[8], s[9]), fmaxf(s[10], s[11])), fmaxf(fmaxf(s[12], s[13]), fmaxf(s[14], s[15])))); }
; DI bf16x8 packp(const f32x16& p, const int s2) { u32x4 w; w.x = cvtpk(p[8 * s2], p[8 * s2 + 1]); w.y = cvtpk(p[8 * s2 + 2], p[8 * s2 + 3]); w.z = cvtpk(p[8 * s2 + 4], p[8 * s2 + 5]); w.w = cvtpk(p[8 * s2 + 6], p[8 * s2 + 7]); return __builtin_bit_cast(bf16x8, w); }
; #define SB() __builtin_amdgcn_sched_barrier(0)
; template <bool FAST> DI bool mla_unit(unsigned char* lds, unsigned char* ws, int seq, int head, int qb, int S, int tid, int wave, int lane) {
;     ...
;             MLA_QK(sB, kaB); MLA_SMF(sA, paA, pbA); MLA_VL(vaA, vcA, 0); MLA_KL(kaA, 2);
;             MLA_PV(vaA, vcA, paA, pbA); MLA_QK(sA, kaA); MLA_SMF(sB, paB, pbB); MLA_VL(vaB, vcB, 1); MLA_KL(kaB, 3);
;             MLA_PV(vaB, vcB, paB, pbB); MLA_QK(sB, kaB); MLA_SMF(sA, paA, pbA); MLA_VL(vaA, vcA, 2);
;             MLA_PV(vaA, vcA, paA, pbA); MLA_SMF(sB, paB, pbB); MLA_VL(vaB, vcB, 3);
;             MLA_PV(vaB, vcB, paB, pbB);
;         } else {
; #pragma unroll
;             for (int t = 0; t < 2; ++t) {
;                 bf16x8 kaA[6], kaB[6], vaA[2], vcA[2], vaB[2], vcB[2]; f32x16 s0, s1;
;                 MLA_KL(kaA, 2 * t); MLA_KL(kaB, 2 * t + 1); MLA_QK(s0, kaA); MLA_QK(s1, kaB); MLA_VL(vaA, vcA, 2 * t); MLA_VL(vaB, vcB, 2 * t + 1);
;                 float mx_ = fmaxf(vmax16(s0), vmax16(s1)); mx_ = fmaxf(mx_, shx(mx_, lane, 32));
;                 const float mnew_ = fmaxf(mrun, mx_), alpha_ = fexp2(mrun - mnew_); mrun = mnew_;
;                 const float ps_ = exp_sum16(s0, mnew_) + exp_sum16(s1, mnew_); lrun = lrun * alpha_ + ps_; o0 *= alpha_; o1 *= alpha_;
;                 const bf16x8 p0_ = packp(s0, 0), p1_ = packp(s0, 1), p2_ = packp(s1, 0), p3_ = packp(s1, 1);
;                 MLA_PV(vaA, vcA, p0_, p1_); MLA_PV(vaB, vcB, p2_, p3_);
;             }
;         }
;         SB(); MLA_STORE((it + 1) & 1); SB();
;         __syncthreads();
	v_mfma_f32_32x32x16_bf16 v[48:63], v[194:197], v[84:87], v[48:63]
	v_exp_f32_e32 v194, v37
	v_add_f32_e32 v196, v175, v203
	v_cvt_pk_bf16_f32 v114, v204, v194
	s_waitcnt lgkmcnt(5)
	v_mfma_f32_32x32x16_bf16 v[32:47], v[32:35], v[64:67], 0
	s_nop 6
	v_exp_f32_e32 v199, v48
	v_exp_f32_e32 v203, v49
	v_exp_f32_e32 v187, v56
	v_exp_f32_e32 v185, v57
	v_pk_add_f32 v[48:49], v[198:199], v[148:149]
	v_add_u32_e32 v198, 0x8800, v230
	v_exp_f32_e32 v183, v58
	s_waitcnt lgkmcnt(4)
	v_mfma_f32_32x32x16_bf16 v[32:47], v[234:237], v[68:71], v[32:47]
	v_exp_f32_e32 v181, v59
	ds_read2_b64 v[56:59], v198 offset0:64 offset1:66
	v_exp_f32_e32 v201, v50
	v_exp_f32_e32 v205, v51
	v_exp_f32_e32 v195, v52
	v_exp_f32_e32 v193, v53
	v_exp_f32_e32 v191, v54
	s_waitcnt lgkmcnt(4)
	v_mfma_f32_32x32x16_bf16 v[32:47], v[238:241], v[72:75], v[32:47]
	v_exp_f32_e32 v189, v55
	v_cvt_pk_bf16_f32 v52, v199, v203
	v_add_u32_e32 v199, 0x9800, v230
	v_pk_add_f32 v[48:49], v[202:203], v[48:49]
	v_exp_f32_e32 v179, v60
	v_exp_f32_e32 v177, v61
	v_exp_f32_e32 v175, v62
	v_mfma_f32_32x32x16_bf16 v[0:15], v[128:131], v[112:115], v[0:15]
	v_exp_f32_e32 v197, v63
	v_pk_add_f32 v[48:49], v[200:201], v[48:49]
	v_cvt_pk_bf16_f32 v53, v201, v205
	v_pk_add_f32 v[128:129], v[204:205], v[48:49]
	v_cvt_pk_bf16_f32 v54, v195, v193
	v_cvt_pk_bf16_f32 v55, v191, v189
	v_cvt_pk_bf16_f32 v48, v187, v185
	v_mfma_f32_32x32x16_bf16 v[16:31], v[120:123], v[112:115], v[16:31]
	v_add_f32_e64 v120, v194, v128
	v_add_f32_e64 v121, v195, v129
	v_cvt_pk_bf16_f32 v49, v183, v181
	v_add_f32_e64 v120, v192, v120
	v_add_f32_e64 v121, v193, v121
	v_cvt_pk_bf16_f32 v50, v179, v177
	v_pk_add_f32 v[120:121], v[190:191], v[120:121]
	v_cvt_pk_bf16_f32 v51, v175, v197
	v_pk_add_f32 v[120:121], v[188:189], v[120:121]
	s_waitcnt lgkmcnt(3)
	v_mfma_f32_32x32x16_bf16 v[32:47], v[242:245], v[76:79], v[32:47]
	v_add_f32_e64 v120, v186, v120
	v_add_f32_e64 v121, v187, v121
	v_add_f32_e64 v120, v184, v120
	v_add_f32_e64 v121, v185, v121
	v_add_f32_e64 v120, v182, v120
	v_add_f32_e64 v121, v183, v121
	v_pk_add_f32 v[120:121], v[180:181], v[120:121]
	v_mfma_f32_32x32x16_bf16 v[0:15], v[132:135], v[116:119], v[0:15]
	v_add_f32_e64 v120, v178, v120
	v_add_f32_e64 v121, v179, v121
	v_add_f32_e64 v120, v176, v120
	v_add_f32_e64 v121, v177, v121
	v_add_f32_e64 v120, v174, v120
	v_add_f32_e64 v121, v175, v121
	v_pk_add_f32 v[174:175], v[196:197], v[120:121]
	v_mfma_f32_32x32x16_bf16 v[16:31], v[124:127], v[116:119], v[16:31]
	ds_read2_b64 v[112:115], v199 offset0:96 offset1:98
	ds_read2_b64 v[60:63], v198 offset0:68 offset1:70
	ds_read2_b64 v[116:119], v199 offset0:100 offset1:102
	v_add_f32_e32 v120, v174, v175
	s_waitcnt lgkmcnt(5)
	v_mfma_f32_32x32x16_bf16 v[32:47], v[246:249], v[80:83], v[32:47]
	s_waitcnt lgkmcnt(2)
	v_mfma_f32_32x32x16_bf16 v[16:31], v[112:115], v[52:55], v[16:31]
	v_mfma_f32_32x32x16_bf16 v[0:15], v[56:59], v[52:55], v[0:15]
	v_mfma_f32_32x32x16_bf16 v[32:47], v[250:253], v[84:87], v[32:47]
	s_waitcnt lgkmcnt(0)
	v_mfma_f32_32x32x16_bf16 v[16:31], v[116:119], v[48:51], v[16:31]
	s_bitcmp1_b32 s3, 0
	s_cselect_b32 s24, 0xac00, 0
	v_add3_u32 v231, s24, v220, v158
	v_add3_u32 v208, s24, v159, v217
	v_add3_u32 v209, s24, v218, v219
	s_waitcnt vmcnt(5)
	ds_write_b128 v208, v[92:95]
	s_waitcnt vmcnt(4)
	ds_write_b128 v209, v[88:91]
	s_waitcnt vmcnt(3)
	ds_write_b64 v231, v[96:97] offset:13312
	ds_write_b64 v231, v[98:99] offset:13320
	s_waitcnt vmcnt(1)
	ds_write_b128 v208, v[104:107] offset:22016
	s_waitcnt vmcnt(0)
	ds_write_b128 v209, v[108:111] offset:22016
	ds_write_b64 v231, v[100:101] offset:35328
	ds_write_b64 v231, v[102:103] offset:35336
	s_nop 9
	v_exp_f32_e32 v121, v32
	v_exp_f32_e32 v122, v33
	v_exp_f32_e32 v123, v34
	v_exp_f32_e32 v124, v35
	v_exp_f32_e32 v125, v36
	v_exp_f32_e32 v126, v37
	v_exp_f32_e32 v127, v38
	v_mfma_f32_32x32x16_bf16 v[0:15], v[60:63], v[48:51], v[0:15]
	v_exp_f32_e32 v128, v39
	v_exp_f32_e32 v129, v40
	v_exp_f32_e32 v130, v41
	v_exp_f32_e32 v131, v42
	v_exp_f32_e32 v132, v43
	v_exp_f32_e32 v133, v44
	v_exp_f32_e32 v134, v45
	v_exp_f32_e32 v135, v46
	v_exp_f32_e32 v148, v47
	ds_read2_b64 v[116:119], v198 offset0:72 offset1:74
	ds_read2_b64 v[112:115], v199 offset0:104 offset1:106
	ds_read2_b64 v[44:47], v198 offset0:76 offset1:78
	ds_read2_b64 v[40:43], v199 offset0:108 offset1:110
	v_cvt_pk_bf16_f32 v36, v121, v122
	v_cvt_pk_bf16_f32 v37, v123, v124
	v_cvt_pk_bf16_f32 v38, v125, v126
	v_cvt_pk_bf16_f32 v39, v127, v128
	v_add_f32_e32 v121, 0, v121
	v_add_f32_e32 v121, v122, v121
	s_waitcnt lgkmcnt(3)
	v_mfma_f32_32x32x16_bf16 v[0:15], v[116:119], v[36:39], v[0:15]
	v_add_f32_e32 v121, v123, v121
	v_add_f32_e32 v121, v124, v121
	v_add_f32_e32 v121, v125, v121
	v_add_f32_e32 v121, v126, v121
	v_add_f32_e32 v121, v127, v121
	v_add_f32_e32 v121, v128, v121
	v_cvt_pk_bf16_f32 v32, v129, v130
	s_waitcnt lgkmcnt(2)
	v_mfma_f32_32x32x16_bf16 v[16:31], v[112:115], v[36:39], v[16:31]
	v_cvt_pk_bf16_f32 v33, v131, v132
	v_cvt_pk_bf16_f32 v34, v133, v134
	v_cvt_pk_bf16_f32 v35, v135, v148
	v_add_f32_e32 v121, v129, v121
	v_add_f32_e32 v121, v130, v121
	v_add_f32_e32 v121, v131, v121
	v_add_f32_e32 v121, v132, v121
	s_waitcnt lgkmcnt(1)
	v_mfma_f32_32x32x16_bf16 v[0:15], v[44:47], v[32:35], v[0:15]
	v_add_f32_e32 v121, v133, v121
	v_add_f32_e32 v121, v134, v121
	v_add_f32_e32 v121, v135, v121
	v_add_f32_e32 v121, v148, v121
	v_add_f32_e32 v175, v120, v121
	s_waitcnt lgkmcnt(0)
	v_mfma_f32_32x32x16_bf16 v[16:31], v[40:43], v[32:35], v[16:31]
	s_cmp_lg_u32 s19, s3
	s_waitcnt lgkmcnt(0)
	s_barrier
; DI unsigned cvtpk(float lo, float hi) { f32x2_t v = {lo, hi}; bf16x2_t b = __builtin_convertvector(v, bf16x2_t); return __builtin_bit_cast(unsigned, b); }
; DI float shx(float v, int lane, int mask) { return __builtin_bit_cast(float, __builtin_amdgcn_ds_bpermute((lane ^ mask) << 2, __builtin_bit_cast(int, v))); }
; #define MLA_STORE(slot) do { unsigned char* sb_ = lds + (slot) * MLA_SLOT; MLA_ST1(sb_, kA0, kB0, vv0); MLA_ST1(sb_ + MLA_BUF, kA1, kB1, vv1); } while (0)
; template <bool FAST> DI bool mla_unit(unsigned char* lds, unsigned char* ws, int seq, int head, int qb, int S, int tid, int wave, int lane) {
;     const bf16_t* Q = (const bf16_t*)(ws + WS_Q); const bf16_t* K = (const bf16_t*)(ws + WS_K); const bf16_t* VT = (const bf16_t*)(ws + WS_VT); bf16_t* BB = (bf16_t*)(ws + WS_BR) + 512;
;     const int r = lane & 31, h = lane >> 5;
;     const size_t tokq = (size_t)seq * S + qb * 256 + wave * 32 + r;
;     const bf16_t* qp = Q + tokq * 768 + head * 96 + 8 * h;
;     bf16x8 qf[6];
; #pragma unroll
;     for (int s = 0; s < 6; ++s) qf[s] = *(const bf16x8*)(qp + 16 * s);
;     f32x16 o0 = zero16(), o1 = zero16(); float mrun = -1e30f, lrun = 0.f;
;     const int kr0 = tid / 12, kc0 = tid - kr0 * 12; const int t2_ = tid < 256 ? tid + 512 : tid; const int kr1 = t2_ / 12, kc1 = t2_ - kr1 * 12;
;     const int vr = tid >> 3, vc = tid & 7;
;     const bf16_t* kbase = K + ((size_t)seq * S) * 768 + head * 96;
;     const bf16_t* vbase = VT + ((size_t)(seq * 8 + head) * 64) * S;
;     u32x4 kA0, kB0, vv0, kA1, kB1, vv1;
;     ...
;     const int nit = S >> 7;
;     MLA_LOAD(0); MLA_STORE(0); __syncthreads();
;     ...
;     const float l = lrun + shx(lrun, lane, 32), inv = 1.f / l;
;     const bool bad = !(l > 1e-30f && l < 1e30f) || (PROBE == 20 && FAST);
;     bf16_t* op = BB + tokq * 1536 + head * 64 + 4 * h;
; #pragma unroll
;     for (int g4 = 0; g4 < 4; ++g4) { u32x2 w; w.x = cvtpk(o0[4 * g4] * inv, o0[4 * g4 + 1] * inv); w.y = cvtpk(o0[4 * g4 + 2] * inv, o0[4 * g4 + 3] * inv); *(u32x2*)(op + 8 * g4) = w;
;         u32x2 w2; w2.x = cvtpk(o1[4 * g4] * inv, o1[4 * g4 + 1] * inv); w2.y = cvtpk(o1[4 * g4 + 2] * inv, o1[4 * g4 + 3] * inv); *(u32x2*)(op + 32 + 8 * g4) = w2; }
;     return bad;
	s_cbranch_scc1 .LBB0_1008
	ds_bpermute_b32 v32, v224, v175
	s_lshl_b32 s84, s2, 7
	s_mov_b32 s2, 0x7149f2ca
	s_waitcnt lgkmcnt(0)
	v_add_f32_e32 v33, v175, v32
	v_div_scale_f32 v32, s[4:5], v33, v33, 1.0
	v_rcp_f32_e32 v34, v32
	s_nop 0
	v_fma_f32 v35, -v32, v34, 1.0
	v_fmac_f32_e32 v34, v35, v34
	v_div_scale_f32 v35, vcc, 1.0, v33, 1.0
	v_mul_f32_e32 v36, v35, v34
	v_fma_f32 v37, -v32, v36, v35
	v_fmac_f32_e32 v36, v37, v34
	v_fma_f32 v32, -v32, v36, v35
	v_div_fmas_f32 v32, v32, v34, v36
	v_mov_b64_e32 v[34:35], s[12:13]
	v_mad_u64_u32 v[34:35], s[4:5], v146, s91, v[34:35]
	v_mov_b32_e32 v36, v35
	v_mad_u64_u32 v[36:37], s[4:5], v147, s91, v[36:37]
	v_div_fixup_f32 v32, v32, v33, 1.0
	v_mov_b32_e32 v35, v36
	v_lshl_add_u64 v[34:35], v[34:35], 0, s[84:85]
	v_pk_mul_f32 v[0:1], v[0:1], v[32:33] op_sel_hi:[1,0]
	v_pk_mul_f32 v[2:3], v[2:3], v[32:33] op_sel_hi:[1,0]
	v_lshl_add_u64 v[174:175], v[162:163], 1, v[34:35]
	v_cvt_pk_bf16_f32 v0, v0, v1
	v_cvt_pk_bf16_f32 v1, v2, v3
	global_store_dwordx2 v[174:175], v[0:1], off
	v_pk_mul_f32 v[0:1], v[16:17], v[32:33] op_sel_hi:[1,0]
	v_pk_mul_f32 v[2:3], v[18:19], v[32:33] op_sel_hi:[1,0]
	v_cvt_pk_bf16_f32 v0, v0, v1
	v_cvt_pk_bf16_f32 v1, v2, v3
	global_store_dwordx2 v[174:175], v[0:1], off offset:64
	v_pk_mul_f32 v[0:1], v[4:5], v[32:33] op_sel_hi:[1,0]
	v_pk_mul_f32 v[2:3], v[6:7], v[32:33] op_sel_hi:[1,0]
	v_cvt_pk_bf16_f32 v0, v0, v1
	v_cvt_pk_bf16_f32 v1, v2, v3
	global_store_dwordx2 v[174:175], v[0:1], off offset:16
	v_pk_mul_f32 v[0:1], v[20:21], v[32:33] op_sel_hi:[1,0]
	v_pk_mul_f32 v[2:3], v[22:23], v[32:33] op_sel_hi:[1,0]
	v_cvt_pk_bf16_f32 v0, v0, v1
	v_cvt_pk_bf16_f32 v1, v2, v3
	global_store_dwordx2 v[174:175], v[0:1], off offset:80
	v_pk_mul_f32 v[0:1], v[8:9], v[32:33] op_sel_hi:[1,0]
	v_pk_mul_f32 v[2:3], v[10:11], v[32:33] op_sel_hi:[1,0]
	v_cvt_pk_bf16_f32 v0, v0, v1
	v_cvt_pk_bf16_f32 v1, v2, v3
	global_store_dwordx2 v[174:175], v[0:1], off offset:32
	v_pk_mul_f32 v[0:1], v[24:25], v[32:33] op_sel_hi:[1,0]
	v_pk_mul_f32 v[2:3], v[26:27], v[32:33] op_sel_hi:[1,0]
	v_cvt_pk_bf16_f32 v0, v0, v1
	v_cvt_pk_bf16_f32 v1, v2, v3
	global_store_dwordx2 v[174:175], v[0:1], off offset:96
	v_pk_mul_f32 v[0:1], v[12:13], v[32:33] op_sel_hi:[1,0]
	v_pk_mul_f32 v[2:3], v[14:15], v[32:33] op_sel_hi:[1,0]
	v_cvt_pk_bf16_f32 v0, v0, v1
	v_cvt_pk_bf16_f32 v1, v2, v3
	v_cmp_ngt_f32_e32 vcc, s2, v33
	s_mov_b32 s2, 0xda24260
	global_store_dwordx2 v[174:175], v[0:1], off offset:48
	v_pk_mul_f32 v[0:1], v[28:29], v[32:33] op_sel_hi:[1,0]
	v_pk_mul_f32 v[2:3], v[30:31], v[32:33] op_sel_hi:[1,0]
	v_cmp_nlt_f32_e64 s[8:9], s2, v33
	v_cvt_pk_bf16_f32 v0, v0, v1
	v_cvt_pk_bf16_f32 v1, v2, v3
	s_or_b64 s[2:3], s[8:9], vcc
	global_store_dwordx2 v[174:175], v[0:1], off offset:112
	s_and_saveexec_b64 s[4:5], s[2:3]
	v_mov_b32_e32 v0, s33
	ds_write_b32 v0, v210
	s_or_b64 exec, exec, s[4:5]
	v_mov_b32_e32 v0, s33
	s_waitcnt lgkmcnt(0)
	s_barrier
	ds_read_b32 v0, v0
	s_waitcnt lgkmcnt(0)
	s_barrier
	v_cmp_eq_u32_e32 vcc, 0, v0
	s_cbranch_vccnz .LBB0_1004
	global_load_dwordx4 v[64:67], v[136:137], off
	global_load_dwordx4 v[68:71], v[136:137], off offset:32
	global_load_dwordx4 v[72:75], v[136:137], off offset:64
	global_load_dwordx4 v[76:79], v[136:137], off offset:96
	global_load_dwordx4 v[80:83], v[136:137], off offset:128
	global_load_dwordx4 v[84:87], v[136:137], off offset:160
	global_load_dwordx4 v[0:3], v[138:139], off
	global_load_dwordx4 v[4:7], v[140:141], off
	global_load_dwordx4 v[8:11], v[168:169], off
	global_load_dwordx4 v[12:15], v[142:143], off
	global_load_dwordx4 v[16:19], v[144:145], off
	global_load_dwordx4 v[20:23], v[168:169], off offset:128
	v_mov_b32_e32 v189, 0
	s_mov_b32 s4, 0
	v_mov_b32_e32 v188, 0xf149f2ca
	v_mov_b32_e32 v24, v189
	v_mov_b32_e32 v25, v189
	v_mov_b32_e32 v26, v189
	v_mov_b32_e32 v27, v189
	v_mov_b32_e32 v28, v189
	v_mov_b32_e32 v29, v189
	v_mov_b32_e32 v30, v189
	v_mov_b32_e32 v31, v189
	s_waitcnt vmcnt(5)
	ds_write_b128 v225, v[0:3]
	s_waitcnt vmcnt(4)
	ds_write_b128 v226, v[4:7]
	s_waitcnt vmcnt(3)
	ds_write2_b64 v228, v[8:9], v[10:11] offset1:1
	s_waitcnt vmcnt(2)
	ds_write_b128 v225, v[12:15] offset:22016
	s_waitcnt vmcnt(1)
	ds_write_b128 v226, v[16:19] offset:22016
	s_waitcnt vmcnt(0)
	ds_write2_b64 v229, v[20:21], v[22:23] offset1:1
	v_mov_b32_e32 v16, 0
	v_mov_b32_e32 v17, v189
	v_mov_b32_e32 v18, v189
	v_mov_b32_e32 v19, v189
	v_mov_b32_e32 v20, v189
	v_mov_b32_e32 v21, v189
	v_mov_b32_e32 v22, v189
	v_mov_b32_e32 v23, v189
	v_mov_b32_e32 v0, 0
	v_mov_b32_e32 v1, v189
	v_mov_b32_e32 v2, v189
	v_mov_b32_e32 v3, v189
	v_mov_b32_e32 v4, v189
	v_mov_b32_e32 v5, v189
	v_mov_b32_e32 v6, v189
	v_mov_b32_e32 v7, v189
	v_mov_b32_e32 v8, v189
	v_mov_b32_e32 v9, v189
	v_mov_b32_e32 v10, v189
	v_mov_b32_e32 v11, v189
	v_mov_b32_e32 v12, v189
	v_mov_b32_e32 v13, v189
	v_mov_b32_e32 v14, v189
	v_mov_b32_e32 v15, v189
	s_waitcnt lgkmcnt(0)
	s_barrier
